# attention unit prologue: queue atomic, 4 Q-norm loads and key-norm load issued together behind one wait (were 6 serialized round trips)
# speedup vs baseline: 1.2502x; 1.2502x over previous
.LBB0_129:
	v_mov_b32_e32 v32, v200
	v_mov_b32_e32 v12, 0
	v_cmp_eq_u32_e32 vcc, 0, v32
	s_and_saveexec_b64 s[4:5], vcc
	s_cbranch_execz .LBB0_133
	s_mov_b64 s[12:13], exec
	v_mbcnt_lo_u32_b32 v38, s12, 0
	v_mbcnt_hi_u32_b32 v38, s13, v38
	v_cmp_eq_u32_e64 s[2:3], 0, v38
	s_and_saveexec_b64 s[6:7], s[2:3]
	s_cbranch_execz .LBB0_132
	s_bcnt1_i32_b64 s2, s[12:13]
	v_mov_b32_e32 v39, s2
	global_atomic_add v39, v193, v39, s[8:9] sc0
.LBB0_132:
	s_or_b64 exec, exec, s[6:7]
.LBB0_133:
	s_or_b64 exec, exec, s[4:5]
	s_and_b32 s18, s20, 63
	s_lshl_b32 s2, s18, 14
	v_readlane_b32 s4, v252, 30
	v_readlane_b32 s5, v252, 31
	s_add_u32 s2, s4, s2
	s_addc_u32 s3, s5, 0
	s_and_b32 s4, s20, 0xffffffc0
	s_sub_i32 s12, 0x400, s4
	v_cmp_gt_i32_e64 s[6:7], s12, v32
	v_mov_b32_e32 v0, 0
	v_mov_b32_e32 v4, 0
	v_mov_b32_e32 v5, 0
	v_mov_b32_e32 v6, 0
	v_mov_b32_e32 v7, 0
	s_and_saveexec_b64 s[4:5], s[6:7]
	s_cbranch_execz .LBB0_135
	v_ashrrev_i32_e32 v33, 31, v32
	v_lshl_add_u64 v[2:3], v[32:33], 4, s[2:3]
	global_load_dwordx4 v[4:7], v[2:3], off

.LBB0_137:
	s_or_b64 exec, exec, s[12:13]
	s_ashr_i32 s16, s20, 6
	s_sub_i32 s19, 15, s16
	s_lshr_b32 s15, s18, 4
	s_lshl_b32 s17, s15, 12
	s_lshl_b32 s14, s19, 8
	s_add_u32 s2, s17, s14
	s_addc_u32 s3, 0, 0
	v_lshl_add_u64 v[10:11], s[2:3], 0, v[202:203]
	v_readlane_b32 s2, v252, 23
	v_lshlrev_b64 v[10:11], 11, v[10:11]
	v_readlane_b32 s3, v252, 24
	s_mov_b32 s13, s79
	s_nop 0
	v_lshl_add_u64 v[10:11], s[2:3], 0, v[10:11]
	s_lshl_b32 s2, s20, 6
	s_and_b32 s2, s2, 0x3c0
	s_lshl_b32 s12, s2, 1
	v_lshl_add_u64 v[10:11], v[10:11], 0, s[12:13]
	v_lshl_add_u64 v[10:11], v[10:11], 0, v[192:193]
	global_load_dwordx4 v[14:17], v[10:11], off
	global_load_dwordx4 v[18:21], v[10:11], off offset:32
	global_load_dwordx4 v[22:25], v[10:11], off offset:64
	global_load_dwordx4 v[26:29], v[10:11], off offset:96
	s_lshl_b32 s2, s18, 3
	v_mov_b32_e32 v30, s2
	global_load_dwordx2 v[34:35], v30, s[10:11]
	v_cmp_lt_i32_e64 s[2:3], v237, v231
	s_waitcnt vmcnt(0)
	v_and_b32_e32 v31, 0xffff0000, v14
	v_lshlrev_b32_e32 v30, 16, v14
	v_mul_f32_e32 v31, v31, v31
	v_fmac_f32_e32 v31, v30, v30
	v_and_b32_e32 v13, 0xffff0000, v15
	v_lshlrev_b32_e32 v30, 16, v15
	v_mul_f32_e32 v13, v13, v13
	v_fmac_f32_e32 v13, v30, v30
	v_add_f32_e32 v9, v31, v13
	v_and_b32_e32 v13, 0xffff0000, v16
	v_lshlrev_b32_e32 v30, 16, v16
	v_mul_f32_e32 v13, v13, v13
	v_fmac_f32_e32 v13, v30, v30
	v_add_f32_e32 v9, v13, v9
	v_and_b32_e32 v13, 0xffff0000, v17
	v_lshlrev_b32_e32 v30, 16, v17
	v_mul_f32_e32 v13, v13, v13
	v_fmac_f32_e32 v13, v30, v30
	v_add_f32_e32 v9, v13, v9
	v_and_b32_e32 v13, 0xffff0000, v18
	v_lshlrev_b32_e32 v30, 16, v18
	v_mul_f32_e32 v13, v13, v13
	v_fmac_f32_e32 v13, v30, v30
	v_add_f32_e32 v9, v13, v9
	v_and_b32_e32 v13, 0xffff0000, v19
	v_lshlrev_b32_e32 v30, 16, v19
	v_mul_f32_e32 v13, v13, v13
	v_fmac_f32_e32 v13, v30, v30
	v_add_f32_e32 v9, v13, v9
	v_and_b32_e32 v13, 0xffff0000, v20
	v_lshlrev_b32_e32 v30, 16, v20
	v_mul_f32_e32 v13, v13, v13
	v_fmac_f32_e32 v13, v30, v30
	v_add_f32_e32 v9, v13, v9
	v_and_b32_e32 v13, 0xffff0000, v21
	v_lshlrev_b32_e32 v30, 16, v21
	v_mul_f32_e32 v13, v13, v13
	v_fmac_f32_e32 v13, v30, v30
	v_add_f32_e32 v9, v13, v9
	v_and_b32_e32 v13, 0xffff0000, v22
	v_lshlrev_b32_e32 v30, 16, v22
	v_mul_f32_e32 v13, v13, v13
	v_fmac_f32_e32 v13, v30, v30
	v_add_f32_e32 v9, v13, v9
	v_and_b32_e32 v13, 0xffff0000, v23
	v_lshlrev_b32_e32 v30, 16, v23
	v_mul_f32_e32 v13, v13, v13
	v_fmac_f32_e32 v13, v30, v30
	v_add_f32_e32 v9, v13, v9
	v_and_b32_e32 v13, 0xffff0000, v24
	v_lshlrev_b32_e32 v30, 16, v24
	v_mul_f32_e32 v13, v13, v13
	v_fmac_f32_e32 v13, v30, v30
	v_add_f32_e32 v9, v13, v9
	v_and_b32_e32 v13, 0xffff0000, v25
	v_lshlrev_b32_e32 v30, 16, v25
	v_mul_f32_e32 v13, v13, v13
	v_fmac_f32_e32 v13, v30, v30
	v_add_f32_e32 v9, v13, v9
	v_and_b32_e32 v13, 0xffff0000, v26
	v_lshlrev_b32_e32 v30, 16, v26
	v_mul_f32_e32 v13, v13, v13
	v_fmac_f32_e32 v13, v30, v30
	v_add_f32_e32 v9, v13, v9
	v_and_b32_e32 v13, 0xffff0000, v27
	v_lshlrev_b32_e32 v30, 16, v27
	v_mul_f32_e32 v13, v13, v13
	v_fmac_f32_e32 v13, v30, v30
	v_add_f32_e32 v9, v13, v9
	v_and_b32_e32 v13, 0xffff0000, v28
	v_lshlrev_b32_e32 v30, 16, v28
	v_mul_f32_e32 v13, v13, v13
	v_fmac_f32_e32 v13, v30, v30
	v_add_f32_e32 v9, v13, v9
	v_and_b32_e32 v13, 0xffff0000, v29
	v_lshlrev_b32_e32 v30, 16, v29
	v_mul_f32_e32 v13, v13, v13
	v_fmac_f32_e32 v13, v30, v30
	v_add_f32_e32 v9, v13, v9
	v_cndmask_b32_e64 v10, v228, v237, s[2:3]
	v_lshlrev_b32_e32 v10, 2, v10
	ds_bpermute_b32 v10, v10, v9
	v_cmp_lt_i32_e64 s[2:3], v232, v231
	s_waitcnt lgkmcnt(0)
	v_add_f32_e32 v9, v9, v10
	v_cndmask_b32_e64 v10, v228, v232, s[2:3]
	v_lshlrev_b32_e32 v10, 2, v10
	ds_bpermute_b32 v10, v10, v9
	v_cmp_lt_i32_e64 s[2:3], v233, v231
	s_waitcnt lgkmcnt(0)
	v_max_f32_e32 v10, v10, v10
	v_max_f32_e32 v9, v9, v10
	v_cndmask_b32_e64 v10, v228, v233, s[2:3]
	v_lshlrev_b32_e32 v10, 2, v10
	ds_bpermute_b32 v10, v10, v9
	v_cmp_lt_i32_e64 s[2:3], v234, v231
	s_waitcnt lgkmcnt(0)
	v_max_f32_e32 v10, v10, v10
	v_max_f32_e32 v9, v9, v10
	v_cndmask_b32_e64 v10, v228, v234, s[2:3]
	v_lshlrev_b32_e32 v10, 2, v10
	ds_bpermute_b32 v10, v10, v9
	v_cmp_lt_i32_e64 s[2:3], v235, v231
	s_waitcnt lgkmcnt(0)
	v_max_f32_e32 v10, v10, v10
	v_max_f32_e32 v9, v9, v10
	v_cndmask_b32_e64 v10, v228, v235, s[2:3]
	v_lshlrev_b32_e32 v10, 2, v10
	ds_bpermute_b32 v10, v10, v9
	v_cmp_lt_i32_e64 s[2:3], v236, v231
	s_waitcnt lgkmcnt(0)
	v_max_f32_e32 v10, v10, v10
	v_max_f32_e32 v9, v9, v10
	v_cndmask_b32_e64 v10, v228, v236, s[2:3]
	v_lshlrev_b32_e32 v10, 2, v10
	ds_bpermute_b32 v10, v10, v9
	s_and_saveexec_b64 s[2:3], s[6:7]
	s_cbranch_execnz .LBB0_162
	s_or_b64 exec, exec, s[2:3]
	s_and_saveexec_b64 s[2:3], s[4:5]
	s_cbranch_execnz .LBB0_163

.LBB0_141:
	s_waitcnt vmcnt(0)
	v_readfirstlane_b32 s32, v39
	s_nop 1
	v_add_u32_e32 v12, s32, v38
	v_add_u32_e32 v0, s65, v12
	v_mov_b32_e32 v1, s68
	ds_write_b32 v1, v0
.LBB0_142:
	s_or_b64 exec, exec, s[2:3]
	s_lshl_b32 s6, s19, 2
	s_add_i32 s2, s6, 4
	v_cmp_gt_u32_e32 vcc, s2, v244
	s_mov_b64 s[2:3], 0
	s_waitcnt lgkmcnt(0)
	s_barrier
	s_and_saveexec_b64 s[4:5], vcc
	s_cbranch_execz .LBB0_144
	v_readlane_b32 s2, v253, 33
	s_nop 1
	v_mov_b32_e32 v0, s2
	ds_read_b128 v[0:3], v0
	v_readlane_b32 s2, v253, 34
	s_waitcnt lgkmcnt(0)
	v_max_f32_e32 v1, v1, v1
	v_max_f32_e32 v0, v0, v0
	v_max_f32_e32 v0, v0, v1
	v_max3_f32 v4, v0, v2, v3
	v_mov_b32_e32 v0, s2
	ds_read_b128 v[0:3], v0
	s_lshl_b32 s2, s18, 3
	s_waitcnt lgkmcnt(0)
	v_max3_f32 v0, v4, v0, v1
	v_max3_f32 v2, v0, v2, v3
	v_add_f32_e32 v0, v34, v35
	v_mul_f32_e32 v0, v2, v0
	v_cmp_gt_f32_e32 vcc, s61, v0
	v_mul_f32_e32 v1, 0x4f800000, v0
	s_nop 0
	v_cndmask_b32_e32 v0, v0, v1, vcc
	v_sqrt_f32_e32 v1, v0
	s_nop 0
	v_add_u32_e32 v2, -1, v1
	v_fma_f32 v3, -v2, v1, v0
	v_cmp_ge_f32_e64 s[2:3], 0, v3
	v_add_u32_e32 v3, 1, v1
	s_nop 0
	v_cndmask_b32_e64 v2, v1, v2, s[2:3]
	v_fma_f32 v1, -v3, v1, v0
	v_cmp_lt_f32_e64 s[2:3], 0, v1
	s_nop 1
	v_cndmask_b32_e64 v1, v2, v3, s[2:3]
	v_mul_f32_e32 v2, 0x37800000, v1
	v_cndmask_b32_e32 v1, v1, v2, vcc
	v_cmp_class_f32_e32 vcc, v0, v226
	s_lshl_b32 s2, s14, 2
	s_add_i32 s3, 0, 0x14800
	v_cndmask_b32_e32 v0, v1, v0, vcc
	s_add_i32 s2, s3, s2
	v_add_f32_e32 v0, v0, v0
	v_mov_b32_e32 v2, 0x42800000
	v_mov_b32_e32 v1, s2
	v_fmamk_f32 v0, v0, 0x3f8020c5, v2
	v_add_u32_e32 v2, s3, v201
	ds_read_b32 v1, v1
	ds_read_b32 v2, v2 offset:252
	s_waitcnt lgkmcnt(0)
	v_sub_f32_e32 v1, v1, v2
	v_cmp_gt_f32_e32 vcc, v1, v0
	s_and_b64 s[2:3], vcc, exec
